# out-projection epilogue: per-row gss loads hoisted to the epilogue head (12 serialized load+store drains removed per tile)
# baseline (speedup 1.0000x reference)
; __device__ __forceinline__ unsigned pk_f16(float lo, float hi) { f32x2 v = {lo, hi}; f16x2_t h = __builtin_convertvector(v, f16x2_t); return __builtin_bit_cast(unsigned, h); }
; __device__ __forceinline__ f32x2 up_f16(unsigned w) { return __builtin_convertvector(__builtin_bit_cast(f16x2_t, w), f32x2); }
;     __device__ __forceinline__ void operator()(const f32x4 (&acc)[2][2][4][2], const Unit& u, int wr, int wc, int fr, int fq) const {
;     ...
; #pragma unroll
;         for (int bj = 0; bj < 2; ++bj) {
;             f32x4 gv[2];
; #pragma unroll
;             for (int n = 0; n < 2; ++n) gv[n] = *(const f32x4*)(gate + (size_t)b * gstride + col0 + bj * HALF + 4 * n);
;             u32x4 pq[2][4];
; #pragma unroll
;             for (int ai = 0; ai < 2; ++ai)
; #pragma unroll
;                 for (int m = 0; m < 4; ++m) pq[ai][m] = *(const u32x4*)(base + (size_t)(row0 + ai * HALF + m * 16) * 1024 + col0 + bj * HALF);
;             asm volatile("" ::: "memory");
; #pragma unroll
;             for (int ai = 0; ai < 2; ++ai) {
; #pragma unroll
;                 for (int m = 0; m < 4; ++m) { const size_t off = (size_t)(row0 + ai * HALF + m * 16) * 1024 + col0 + bj * HALF;
;                     float rc = 1.0f; if constexpr (GN) rc = rsqrtf(gss[2 * 32768 + row0 + ai * HALF + m * 16] * (1.0f / 384.0f) + 1e-6f);
;                     const u32x4 q = pq[ai][m];
;                     const f32x2 qa_ = up_f16(q.x), qb_ = up_f16(q.y), qc_ = up_f16(q.z), qd_ = up_f16(q.w);
;                     const f32x4 x0 = (f32x4){qa_[0], qa_[1], qb_[0], qb_[1]} + gv[0] * (acc[ai][bj][m][0] * rc),
;                                 x1 = (f32x4){qc_[0], qc_[1], qd_[0], qd_[1]} + gv[1] * (acc[ai][bj][m][1] * rc);
;                     { u32x4 wx; wx.x = pk_f16(x0[0], x0[1]); wx.y = pk_f16(x0[2], x0[3]); wx.z = pk_f16(x1[0], x1[1]); wx.w = pk_f16(x1[2], x1[3]); *(u32x4*)(out + off) = wx; }
.LBB0_806:
	s_lshl_b32 s1, s68, 8
	v_mov_b32_e32 v128, v237
	s_ashr_i32 s0, s69, 6
	s_or_b32 s1, s1, s29
	v_or_b32_e32 v140, 16, v186
	v_lshl_add_u32 v138, v128, 3, s1
	s_mul_hi_i32 s1, s0, 0x6000
	s_mulk_i32 s0, 0x6000
	s_add_u32 s0, s20, s0
	v_ashrrev_i32_e32 v139, 31, v138
	s_addc_u32 s1, s21, s1
	v_ashrrev_i32_e32 v141, 31, v140
	v_lshlrev_b64 v[208:209], 11, v[186:187]
	v_lshl_add_u64 v[190:191], v[138:139], 2, s[0:1]
	v_lshlrev_b64 v[246:247], 11, v[140:141]
	v_or_b32_e32 v140, 32, v186
	s_mov_b64 s[0:1], 0x48000
	v_ashrrev_i32_e32 v141, 31, v140
	v_lshl_add_u64 v[220:221], v[208:209], 0, s[0:1]
	s_mov_b64 s[0:1], 0x50000
	s_mov_b64 s[4:5], 0x40000
	v_lshlrev_b64 v[206:207], 1, v[138:139]
	v_lshlrev_b64 v[248:249], 11, v[140:141]
	v_or_b32_e32 v140, 48, v186
	v_lshl_add_u64 v[222:223], v[208:209], 0, s[0:1]
	s_mov_b64 s[0:1], 0x58000
	v_lshl_add_u64 v[218:219], v[208:209], 0, s[4:5]
	v_lshl_add_u64 v[138:139], s[96:97], 0, v[206:207]
	v_ashrrev_i32_e32 v141, 31, v140
	v_lshl_add_u64 v[216:217], v[208:209], 0, s[0:1]
	s_mov_b32 s0, 0x40000
	v_lshl_add_u64 v[192:193], v[138:139], 0, v[208:209]
	v_lshl_add_u64 v[196:197], v[138:139], 0, v[248:249]
	v_lshlrev_b64 v[224:225], 11, v[140:141]
	v_lshl_add_u64 v[200:201], v[138:139], 0, v[218:219]
	v_lshl_add_u64 v[204:205], v[138:139], 0, v[222:223]
	v_add_co_u32_e32 v188, vcc, s0, v188
	global_load_dwordx4 v[130:133], v[190:191], off offset:16
	global_load_dwordx4 v[134:137], v[190:191], off
	v_lshl_add_u64 v[194:195], v[138:139], 0, v[246:247]
	global_load_dwordx4 v[212:215], v[192:193], off
	global_load_dwordx4 v[242:245], v[194:195], off
	v_lshl_add_u64 v[198:199], v[138:139], 0, v[224:225]
	global_load_dwordx4 v[158:161], v[196:197], off
	global_load_dwordx4 v[154:157], v[198:199], off
	v_lshl_add_u64 v[202:203], v[138:139], 0, v[220:221]
	global_load_dwordx4 v[150:153], v[200:201], off
	global_load_dwordx4 v[146:149], v[202:203], off
	v_lshl_add_u64 v[210:211], v[138:139], 0, v[216:217]
	global_load_dwordx4 v[142:145], v[204:205], off
	global_load_dwordx4 v[138:141], v[210:211], off
	v_addc_co_u32_e32 v189, vcc, 0, v189, vcc
	global_load_dword v128, v[188:189], off
	global_load_dword v163, v[188:189], off offset:64
	global_load_dword v165, v[188:189], off offset:128
	global_load_dword v167, v[188:189], off offset:192
	global_load_dword v169, v[188:189], off offset:512
	global_load_dword v171, v[188:189], off offset:576
	global_load_dword v173, v[188:189], off offset:640
	v_lshl_add_u64 v[208:209], s[96:97], 0, v[208:209]
	v_lshl_add_u64 v[208:209], v[208:209], 0, v[206:207]
	s_waitcnt vmcnt(0)
	v_cvt_f32_f16_e32 v250, v212
	v_cvt_f32_f16_sdwa v251, v212 dst_sel:DWORD dst_unused:UNUSED_PAD src0_sel:WORD_1
	v_cvt_f32_f16_e32 v212, v213
	v_cvt_f32_f16_sdwa v213, v213 dst_sel:DWORD dst_unused:UNUSED_PAD src0_sel:WORD_1
	v_cvt_f32_f16_e32 v174, v214
	v_fmamk_f32 v128, v128, 0x3b2aaaab, v227
	v_mul_f32_e32 v175, 0x4b800000, v128
	v_cmp_gt_f32_e32 vcc, s36, v128
	s_nop 1
	v_cndmask_b32_e32 v128, v128, v175, vcc
	v_rsq_f32_e32 v128, v128
	v_cvt_f32_f16_sdwa v175, v214 dst_sel:DWORD dst_unused:UNUSED_PAD src0_sel:WORD_1
	v_cvt_f32_f16_e32 v214, v215
	v_cvt_f32_f16_sdwa v215, v215 dst_sel:DWORD dst_unused:UNUSED_PAD src0_sel:WORD_1
	v_mul_f32_e32 v176, 0x45800000, v128
	v_cndmask_b32_e32 v128, v128, v176, vcc
	v_pk_mul_f32 v[124:125], v[124:125], v[128:129] op_sel_hi:[1,0]
	v_pk_mul_f32 v[126:127], v[126:127], v[128:129] op_sel_hi:[1,0]
	v_pk_mul_f32 v[176:177], v[120:121], v[128:129] op_sel_hi:[1,0]
	v_pk_mul_f32 v[122:123], v[122:123], v[128:129] op_sel_hi:[1,0]
	v_pk_fma_f32 v[120:121], v[136:137], v[126:127], v[212:213]
	v_pk_fma_f32 v[124:125], v[134:135], v[124:125], v[250:251]
	v_pk_fma_f32 v[122:123], v[132:133], v[122:123], v[214:215]
	v_pk_fma_f32 v[126:127], v[130:131], v[176:177], v[174:175]
	v_cvt_pk_f16_f32 v212, v124, v125
	v_cvt_pk_f16_f32 v213, v120, v121
	v_cvt_pk_f16_f32 v214, v126, v127
	v_cvt_pk_f16_f32 v215, v122, v123
	global_store_dwordx4 v[208:209], v[212:215], off
	s_nop 0
	v_lshl_add_u64 v[174:175], s[96:97], 0, v[246:247]
	v_lshl_add_u64 v[212:213], v[174:175], 0, v[206:207]
	v_cvt_f32_f16_e32 v174, v242
	v_cvt_f32_f16_sdwa v175, v242 dst_sel:DWORD dst_unused:UNUSED_PAD src0_sel:WORD_1
	v_cvt_f32_f16_e32 v176, v243
	v_cvt_f32_f16_sdwa v177, v243 dst_sel:DWORD dst_unused:UNUSED_PAD src0_sel:WORD_1
	v_cvt_f32_f16_e32 v214, v244
	v_cvt_f32_f16_e32 v242, v245
	v_cvt_f32_f16_sdwa v243, v245 dst_sel:DWORD dst_unused:UNUSED_PAD src0_sel:WORD_1
	v_fmamk_f32 v128, v163, 0x3b2aaaab, v227
	v_mul_f32_e32 v215, 0x4b800000, v128
	v_cmp_gt_f32_e32 vcc, s36, v128
	s_nop 1
	v_cndmask_b32_e32 v128, v128, v215, vcc
	v_rsq_f32_e32 v128, v128
	v_cvt_f32_f16_sdwa v215, v244 dst_sel:DWORD dst_unused:UNUSED_PAD src0_sel:WORD_1
	v_mul_f32_e32 v241, 0x45800000, v128
	v_cndmask_b32_e32 v128, v128, v241, vcc
	v_pk_mul_f32 v[244:245], v[116:117], v[128:129] op_sel_hi:[1,0]
	v_pk_mul_f32 v[116:117], v[118:119], v[128:129] op_sel_hi:[1,0]
	v_pk_mul_f32 v[246:247], v[112:113], v[128:129] op_sel_hi:[1,0]
	v_pk_mul_f32 v[112:113], v[114:115], v[128:129] op_sel_hi:[1,0]
	v_pk_fma_f32 v[116:117], v[136:137], v[116:117], v[176:177]
	v_pk_fma_f32 v[118:119], v[134:135], v[244:245], v[174:175]
	v_pk_fma_f32 v[112:113], v[132:133], v[112:113], v[242:243]
	v_pk_fma_f32 v[114:115], v[130:131], v[246:247], v[214:215]
	v_cvt_pk_f16_f32 v242, v118, v119
	v_cvt_pk_f16_f32 v243, v116, v117
	v_cvt_pk_f16_f32 v244, v114, v115
	v_cvt_pk_f16_f32 v245, v112, v113
	global_store_dwordx4 v[212:213], v[242:245], off
	s_nop 0
	v_lshl_add_u64 v[174:175], s[96:97], 0, v[248:249]
	v_lshl_add_u64 v[214:215], v[174:175], 0, v[206:207]
; __device__ __forceinline__ unsigned pk_f16(float lo, float hi) { f32x2 v = {lo, hi}; f16x2_t h = __builtin_convertvector(v, f16x2_t); return __builtin_bit_cast(unsigned, h); }
; __device__ __forceinline__ f32x2 up_f16(unsigned w) { return __builtin_convertvector(__builtin_bit_cast(f16x2_t, w), f32x2); }
;     __device__ __forceinline__ void operator()(const f32x4 (&acc)[2][2][4][2], const Unit& u, int wr, int wc, int fr, int fq) const {
;     ...
;             for (int ai = 0; ai < 2; ++ai) {
; #pragma unroll
;                 for (int m = 0; m < 4; ++m) { const size_t off = (size_t)(row0 + ai * HALF + m * 16) * 1024 + col0 + bj * HALF;
;                     float rc = 1.0f; if constexpr (GN) rc = rsqrtf(gss[2 * 32768 + row0 + ai * HALF + m * 16] * (1.0f / 384.0f) + 1e-6f);
;                     const u32x4 q = pq[ai][m];
;                     const f32x2 qa_ = up_f16(q.x), qb_ = up_f16(q.y), qc_ = up_f16(q.z), qd_ = up_f16(q.w);
;                     const f32x4 x0 = (f32x4){qa_[0], qa_[1], qb_[0], qb_[1]} + gv[0] * (acc[ai][bj][m][0] * rc),
;                                 x1 = (f32x4){qc_[0], qc_[1], qd_[0], qd_[1]} + gv[1] * (acc[ai][bj][m][1] * rc);
;                     { u32x4 wx; wx.x = pk_f16(x0[0], x0[1]); wx.y = pk_f16(x0[2], x0[3]); wx.z = pk_f16(x1[0], x1[1]); wx.w = pk_f16(x1[2], x1[3]); *(u32x4*)(out + off) = wx; }
	v_cvt_f32_f16_e32 v174, v158
	v_cvt_f32_f16_sdwa v175, v158 dst_sel:DWORD dst_unused:UNUSED_PAD src0_sel:WORD_1
	v_cvt_f32_f16_e32 v158, v159
	v_cvt_f32_f16_sdwa v159, v159 dst_sel:DWORD dst_unused:UNUSED_PAD src0_sel:WORD_1
	v_cvt_f32_f16_e32 v176, v160
	v_fmamk_f32 v128, v165, 0x3b2aaaab, v227
	v_mul_f32_e32 v177, 0x4b800000, v128
	v_cmp_gt_f32_e32 vcc, s36, v128
	s_nop 1
	v_cndmask_b32_e32 v128, v128, v177, vcc
	v_rsq_f32_e32 v128, v128
	v_cvt_f32_f16_sdwa v177, v160 dst_sel:DWORD dst_unused:UNUSED_PAD src0_sel:WORD_1
	v_cvt_f32_f16_e32 v160, v161
	v_cvt_f32_f16_sdwa v161, v161 dst_sel:DWORD dst_unused:UNUSED_PAD src0_sel:WORD_1
	v_mul_f32_e32 v241, 0x45800000, v128
	v_cndmask_b32_e32 v128, v128, v241, vcc
	v_pk_mul_f32 v[242:243], v[108:109], v[128:129] op_sel_hi:[1,0]
	v_pk_mul_f32 v[108:109], v[110:111], v[128:129] op_sel_hi:[1,0]
	v_pk_mul_f32 v[244:245], v[104:105], v[128:129] op_sel_hi:[1,0]
	v_pk_mul_f32 v[104:105], v[106:107], v[128:129] op_sel_hi:[1,0]
	v_pk_fma_f32 v[108:109], v[136:137], v[108:109], v[158:159]
	v_pk_fma_f32 v[110:111], v[134:135], v[242:243], v[174:175]
	v_pk_fma_f32 v[104:105], v[132:133], v[104:105], v[160:161]
	v_pk_fma_f32 v[106:107], v[130:131], v[244:245], v[176:177]
	v_cvt_pk_f16_f32 v158, v110, v111
	v_cvt_pk_f16_f32 v159, v108, v109
	v_cvt_pk_f16_f32 v160, v106, v107
	v_cvt_pk_f16_f32 v161, v104, v105
	global_store_dwordx4 v[214:215], v[158:161], off
	s_nop 0
	v_cvt_f32_f16_e32 v174, v156
	v_cvt_f32_f16_e32 v160, v154
	v_cvt_f32_f16_sdwa v161, v154 dst_sel:DWORD dst_unused:UNUSED_PAD src0_sel:WORD_1
	v_cvt_f32_f16_e32 v154, v155
	v_cvt_f32_f16_sdwa v155, v155 dst_sel:DWORD dst_unused:UNUSED_PAD src0_sel:WORD_1
	v_lshl_add_u64 v[158:159], s[96:97], 0, v[224:225]
	v_lshl_add_u64 v[158:159], v[158:159], 0, v[206:207]
	v_fmamk_f32 v128, v167, 0x3b2aaaab, v227
	v_mul_f32_e32 v175, 0x4b800000, v128
	v_cmp_gt_f32_e32 vcc, s36, v128
	s_nop 1
	v_cndmask_b32_e32 v128, v128, v175, vcc
	v_rsq_f32_e32 v128, v128
	v_cvt_f32_f16_sdwa v175, v156 dst_sel:DWORD dst_unused:UNUSED_PAD src0_sel:WORD_1
	v_cvt_f32_f16_e32 v156, v157
	v_cvt_f32_f16_sdwa v157, v157 dst_sel:DWORD dst_unused:UNUSED_PAD src0_sel:WORD_1
	v_mul_f32_e32 v176, 0x45800000, v128
	v_cndmask_b32_e32 v128, v128, v176, vcc
	v_pk_mul_f32 v[176:177], v[100:101], v[128:129] op_sel_hi:[1,0]
	v_pk_mul_f32 v[100:101], v[102:103], v[128:129] op_sel_hi:[1,0]
	v_pk_mul_f32 v[224:225], v[96:97], v[128:129] op_sel_hi:[1,0]
	v_pk_mul_f32 v[96:97], v[98:99], v[128:129] op_sel_hi:[1,0]
	v_pk_fma_f32 v[100:101], v[136:137], v[100:101], v[154:155]
	v_pk_fma_f32 v[102:103], v[134:135], v[176:177], v[160:161]
	v_pk_fma_f32 v[96:97], v[132:133], v[96:97], v[156:157]
	v_pk_fma_f32 v[98:99], v[130:131], v[224:225], v[174:175]
	v_cvt_pk_f16_f32 v154, v102, v103
	v_cvt_pk_f16_f32 v155, v100, v101
	v_cvt_pk_f16_f32 v156, v98, v99
	v_cvt_pk_f16_f32 v157, v96, v97
	global_store_dwordx4 v[158:159], v[154:157], off
	s_nop 0
	v_fmamk_f32 v128, v169, 0x3b2aaaab, v227
	v_mul_f32_e32 v157, 0x4b800000, v128
	v_cmp_gt_f32_e32 vcc, s36, v128
	v_lshl_add_u64 v[154:155], s[96:97], 0, v[218:219]
	v_lshl_add_u64 v[218:219], v[154:155], 0, v[206:207]
	v_cndmask_b32_e32 v128, v128, v157, vcc
	v_rsq_f32_e32 v128, v128
	v_cvt_f32_f16_e32 v154, v150
	v_cvt_f32_f16_sdwa v155, v150 dst_sel:DWORD dst_unused:UNUSED_PAD src0_sel:WORD_1
	v_cvt_f32_f16_e32 v150, v151
	v_cvt_f32_f16_sdwa v151, v151 dst_sel:DWORD dst_unused:UNUSED_PAD src0_sel:WORD_1
	v_cvt_f32_f16_e32 v156, v152
	v_cvt_f32_f16_sdwa v157, v152 dst_sel:DWORD dst_unused:UNUSED_PAD src0_sel:WORD_1
	v_cvt_f32_f16_e32 v152, v153
	v_cvt_f32_f16_sdwa v153, v153 dst_sel:DWORD dst_unused:UNUSED_PAD src0_sel:WORD_1
	v_mul_f32_e32 v160, 0x45800000, v128
	v_cndmask_b32_e32 v128, v128, v160, vcc
	v_pk_mul_f32 v[160:161], v[92:93], v[128:129] op_sel_hi:[1,0]
	v_pk_mul_f32 v[92:93], v[94:95], v[128:129] op_sel_hi:[1,0]
	v_pk_mul_f32 v[174:175], v[88:89], v[128:129] op_sel_hi:[1,0]
	v_pk_mul_f32 v[88:89], v[90:91], v[128:129] op_sel_hi:[1,0]
	v_pk_fma_f32 v[92:93], v[136:137], v[92:93], v[150:151]
	v_pk_fma_f32 v[94:95], v[134:135], v[160:161], v[154:155]
	v_pk_fma_f32 v[88:89], v[132:133], v[88:89], v[152:153]
	v_pk_fma_f32 v[90:91], v[130:131], v[174:175], v[156:157]
	v_cvt_pk_f16_f32 v150, v94, v95
	v_cvt_pk_f16_f32 v151, v92, v93
	v_cvt_pk_f16_f32 v152, v90, v91
	v_cvt_pk_f16_f32 v153, v88, v89
	global_store_dwordx4 v[218:219], v[150:153], off
	s_nop 0
	v_cvt_f32_f16_e32 v154, v148
	v_lshl_add_u64 v[150:151], s[96:97], 0, v[220:221]
	v_lshl_add_u64 v[220:221], v[150:151], 0, v[206:207]
	v_cvt_f32_f16_e32 v152, v146
	v_cvt_f32_f16_sdwa v153, v146 dst_sel:DWORD dst_unused:UNUSED_PAD src0_sel:WORD_1
	v_cvt_f32_f16_e32 v146, v147
	v_cvt_f32_f16_sdwa v147, v147 dst_sel:DWORD dst_unused:UNUSED_PAD src0_sel:WORD_1
	v_cvt_f32_f16_sdwa v155, v148 dst_sel:DWORD dst_unused:UNUSED_PAD src0_sel:WORD_1
	v_cvt_f32_f16_e32 v148, v149
	v_cvt_f32_f16_sdwa v149, v149 dst_sel:DWORD dst_unused:UNUSED_PAD src0_sel:WORD_1
	v_fmamk_f32 v128, v171, 0x3b2aaaab, v227
	v_mul_f32_e32 v150, 0x4b800000, v128
	v_cmp_gt_f32_e32 vcc, s36, v128
	s_nop 1
	v_cndmask_b32_e32 v128, v128, v150, vcc
	v_rsq_f32_e32 v128, v128
	s_nop 0
	v_mul_f32_e32 v150, 0x45800000, v128
	v_cndmask_b32_e32 v128, v128, v150, vcc
	v_pk_mul_f32 v[84:85], v[84:85], v[128:129] op_sel_hi:[1,0]
	v_pk_mul_f32 v[86:87], v[86:87], v[128:129] op_sel_hi:[1,0]
	v_pk_mul_f32 v[80:81], v[80:81], v[128:129] op_sel_hi:[1,0]
	v_pk_mul_f32 v[82:83], v[82:83], v[128:129] op_sel_hi:[1,0]
	v_pk_fma_f32 v[150:151], v[136:137], v[86:87], v[146:147]
	v_pk_fma_f32 v[152:153], v[134:135], v[84:85], v[152:153]
; __device__ __forceinline__ unsigned pk_f16(float lo, float hi) { f32x2 v = {lo, hi}; f16x2_t h = __builtin_convertvector(v, f16x2_t); return __builtin_bit_cast(unsigned, h); }
; __device__ __forceinline__ f32x2 up_f16(unsigned w) { return __builtin_convertvector(__builtin_bit_cast(f16x2_t, w), f32x2); }
;     __device__ __forceinline__ void operator()(const f32x4 (&acc)[2][2][4][2], const Unit& u, int wr, int wc, int fr, int fq) const {
;     ...
;                 for (int m = 0; m < 4; ++m) pq[ai][m] = *(const u32x4*)(base + (size_t)(row0 + ai * HALF + m * 16) * 1024 + col0 + bj * HALF);
;             asm volatile("" ::: "memory");
; #pragma unroll
;             for (int ai = 0; ai < 2; ++ai) {
; #pragma unroll
;                 for (int m = 0; m < 4; ++m) { const size_t off = (size_t)(row0 + ai * HALF + m * 16) * 1024 + col0 + bj * HALF;
;                     float rc = 1.0f; if constexpr (GN) rc = rsqrtf(gss[2 * 32768 + row0 + ai * HALF + m * 16] * (1.0f / 384.0f) + 1e-6f);
;                     const u32x4 q = pq[ai][m];
;                     const f32x2 qa_ = up_f16(q.x), qb_ = up_f16(q.y), qc_ = up_f16(q.z), qd_ = up_f16(q.w);
;                     const f32x4 x0 = (f32x4){qa_[0], qa_[1], qb_[0], qb_[1]} + gv[0] * (acc[ai][bj][m][0] * rc),
;                                 x1 = (f32x4){qc_[0], qc_[1], qd_[0], qd_[1]} + gv[1] * (acc[ai][bj][m][1] * rc);
;                     { u32x4 wx; wx.x = pk_f16(x0[0], x0[1]); wx.y = pk_f16(x0[2], x0[3]); wx.z = pk_f16(x1[0], x1[1]); wx.w = pk_f16(x1[2], x1[3]); *(u32x4*)(out + off) = wx; }
	v_pk_fma_f32 v[146:147], v[132:133], v[82:83], v[148:149]
	v_pk_fma_f32 v[148:149], v[130:131], v[80:81], v[154:155]
	v_cvt_pk_f16_f32 v80, v152, v153
	v_cvt_pk_f16_f32 v81, v150, v151
	v_cvt_pk_f16_f32 v82, v148, v149
	v_cvt_pk_f16_f32 v83, v146, v147
	global_store_dwordx4 v[220:221], v[80:83], off
	s_nop 0
	v_cvt_f32_f16_e32 v84, v144
	v_lshl_add_u64 v[80:81], s[96:97], 0, v[222:223]
	v_lshl_add_u64 v[222:223], v[80:81], 0, v[206:207]
	v_cvt_f32_f16_e32 v80, v142
	v_cvt_f32_f16_sdwa v81, v142 dst_sel:DWORD dst_unused:UNUSED_PAD src0_sel:WORD_1
	v_cvt_f32_f16_e32 v82, v143
	v_cvt_f32_f16_sdwa v83, v143 dst_sel:DWORD dst_unused:UNUSED_PAD src0_sel:WORD_1
	v_cvt_f32_f16_sdwa v87, v145 dst_sel:DWORD dst_unused:UNUSED_PAD src0_sel:WORD_1
	v_fmamk_f32 v85, v173, 0x3b2aaaab, v227
	v_mul_f32_e32 v86, 0x4b800000, v85
	v_cmp_gt_f32_e32 vcc, s36, v85
	s_nop 1
	v_cndmask_b32_e32 v85, v85, v86, vcc
	v_rsq_f32_e32 v128, v85
	v_cvt_f32_f16_sdwa v85, v144 dst_sel:DWORD dst_unused:UNUSED_PAD src0_sel:WORD_1
	v_cvt_f32_f16_e32 v86, v145
	v_mul_f32_e32 v142, 0x45800000, v128
	v_cndmask_b32_e32 v128, v128, v142, vcc
	v_pk_mul_f32 v[76:77], v[76:77], v[128:129] op_sel_hi:[1,0]
	v_pk_mul_f32 v[78:79], v[78:79], v[128:129] op_sel_hi:[1,0]
	v_pk_mul_f32 v[72:73], v[72:73], v[128:129] op_sel_hi:[1,0]
	v_pk_mul_f32 v[74:75], v[74:75], v[128:129] op_sel_hi:[1,0]
	v_pk_fma_f32 v[154:155], v[136:137], v[78:79], v[82:83]
	v_pk_fma_f32 v[156:157], v[134:135], v[76:77], v[80:81]
	v_pk_fma_f32 v[142:143], v[132:133], v[74:75], v[86:87]
	v_pk_fma_f32 v[144:145], v[130:131], v[72:73], v[84:85]
	v_cvt_pk_f16_f32 v72, v156, v157
	v_cvt_pk_f16_f32 v73, v154, v155
	v_cvt_pk_f16_f32 v74, v144, v145
	v_cvt_pk_f16_f32 v75, v142, v143
	global_store_dwordx4 v[222:223], v[72:75], off
	global_load_dword v77, v[188:189], off offset:704
	v_cvt_f32_f16_e32 v76, v140
	v_lshl_add_u64 v[72:73], s[96:97], 0, v[216:217]
	v_lshl_add_u64 v[160:161], v[72:73], 0, v[206:207]
	v_cvt_f32_f16_e32 v72, v138
	v_cvt_f32_f16_sdwa v73, v138 dst_sel:DWORD dst_unused:UNUSED_PAD src0_sel:WORD_1
	v_cvt_f32_f16_e32 v74, v139
	v_cvt_f32_f16_sdwa v75, v139 dst_sel:DWORD dst_unused:UNUSED_PAD src0_sel:WORD_1
	v_cvt_f32_f16_sdwa v79, v141 dst_sel:DWORD dst_unused:UNUSED_PAD src0_sel:WORD_1
	s_waitcnt vmcnt(0)
	v_fmamk_f32 v77, v77, 0x3b2aaaab, v227
	v_mul_f32_e32 v78, 0x4b800000, v77
	v_cmp_gt_f32_e32 vcc, s36, v77
	s_nop 1
	v_cndmask_b32_e32 v77, v77, v78, vcc
	v_rsq_f32_e32 v80, v77
	v_cvt_f32_f16_sdwa v77, v140 dst_sel:DWORD dst_unused:UNUSED_PAD src0_sel:WORD_1
	v_cvt_f32_f16_e32 v78, v141
	v_mul_f32_e32 v81, 0x45800000, v80
	v_cndmask_b32_e32 v80, v80, v81, vcc
	v_pk_mul_f32 v[68:69], v[68:69], v[80:81] op_sel_hi:[1,0]
	v_pk_mul_f32 v[70:71], v[70:71], v[80:81] op_sel_hi:[1,0]
	v_pk_mul_f32 v[64:65], v[64:65], v[80:81] op_sel_hi:[1,0]
	v_pk_mul_f32 v[66:67], v[66:67], v[80:81] op_sel_hi:[1,0]
	v_pk_fma_f32 v[136:137], v[136:137], v[70:71], v[74:75]
	v_pk_fma_f32 v[134:135], v[134:135], v[68:69], v[72:73]
	v_pk_fma_f32 v[132:133], v[132:133], v[66:67], v[78:79]
	v_pk_fma_f32 v[130:131], v[130:131], v[64:65], v[76:77]
	v_cvt_pk_f16_f32 v64, v134, v135
	v_cvt_pk_f16_f32 v65, v136, v137
	v_cvt_pk_f16_f32 v66, v130, v131
	v_cvt_pk_f16_f32 v67, v132, v133
	global_store_dwordx4 v[160:161], v[64:67], off
	global_load_dwordx4 v[64:67], v[190:191], off offset:528
	global_load_dwordx4 v[68:71], v[190:191], off offset:512
	global_load_dwordx4 v[138:141], v[192:193], off offset:256
	s_nop 0
	global_load_dwordx4 v[190:193], v[194:195], off offset:256
	s_nop 0
	global_load_dwordx4 v[194:197], v[196:197], off offset:256
	s_nop 0
	global_load_dwordx4 v[242:245], v[198:199], off offset:256
	global_load_dwordx4 v[84:87], v[200:201], off offset:256
	global_load_dwordx4 v[80:83], v[202:203], off offset:256
	global_load_dwordx4 v[76:79], v[204:205], off offset:256
	global_load_dwordx4 v[72:75], v[210:211], off offset:256
	global_load_dword v128, v[188:189], off
	s_waitcnt vmcnt(8)
	v_cvt_f32_f16_e32 v174, v138
	v_cvt_f32_f16_sdwa v175, v138 dst_sel:DWORD dst_unused:UNUSED_PAD src0_sel:WORD_1
	v_cvt_f32_f16_e32 v138, v139
	v_cvt_f32_f16_sdwa v139, v139 dst_sel:DWORD dst_unused:UNUSED_PAD src0_sel:WORD_1
	v_cvt_f32_f16_e32 v176, v140
	s_waitcnt vmcnt(0)
; __device__ __forceinline__ unsigned pk_f16(float lo, float hi) { f32x2 v = {lo, hi}; f16x2_t h = __builtin_convertvector(v, f16x2_t); return __builtin_bit_cast(unsigned, h); }
; __device__ __forceinline__ f32x2 up_f16(unsigned w) { return __builtin_convertvector(__builtin_bit_cast(f16x2_t, w), f32x2); }
;     __device__ __forceinline__ void operator()(const f32x4 (&acc)[2][2][4][2], const Unit& u, int wr, int wc, int fr, int fq) const {
;     ...
;             for (int ai = 0; ai < 2; ++ai) {
; #pragma unroll
;                 for (int m = 0; m < 4; ++m) { const size_t off = (size_t)(row0 + ai * HALF + m * 16) * 1024 + col0 + bj * HALF;
;                     float rc = 1.0f; if constexpr (GN) rc = rsqrtf(gss[2 * 32768 + row0 + ai * HALF + m * 16] * (1.0f / 384.0f) + 1e-6f);
;                     const u32x4 q = pq[ai][m];
;                     const f32x2 qa_ = up_f16(q.x), qb_ = up_f16(q.y), qc_ = up_f16(q.z), qd_ = up_f16(q.w);
;                     const f32x4 x0 = (f32x4){qa_[0], qa_[1], qb_[0], qb_[1]} + gv[0] * (acc[ai][bj][m][0] * rc),
;                                 x1 = (f32x4){qc_[0], qc_[1], qd_[0], qd_[1]} + gv[1] * (acc[ai][bj][m][1] * rc);
;                     { u32x4 wx; wx.x = pk_f16(x0[0], x0[1]); wx.y = pk_f16(x0[2], x0[3]); wx.z = pk_f16(x1[0], x1[1]); wx.w = pk_f16(x1[2], x1[3]); *(u32x4*)(out + off) = wx; }
;                     ss[ai][m] += ((x0[0] * x0[0] + x0[1] * x0[1]) + (x0[2] * x0[2] + x0[3] * x0[3])) + ((x1[0] * x1[0] + x1[1] * x1[1]) + (x1[2] * x1[2] + x1[3] * x1[3]));
	v_fmamk_f32 v128, v128, 0x3b2aaaab, v227
	v_mul_f32_e32 v177, 0x4b800000, v128
	v_cmp_gt_f32_e32 vcc, s36, v128
	s_nop 1
	v_cndmask_b32_e32 v128, v128, v177, vcc
	v_rsq_f32_e32 v128, v128
	v_cvt_f32_f16_sdwa v177, v140 dst_sel:DWORD dst_unused:UNUSED_PAD src0_sel:WORD_1
	v_cvt_f32_f16_e32 v140, v141
	v_cvt_f32_f16_sdwa v141, v141 dst_sel:DWORD dst_unused:UNUSED_PAD src0_sel:WORD_1
	v_mul_f32_e32 v198, 0x45800000, v128
	v_cndmask_b32_e32 v128, v128, v198, vcc
	v_pk_mul_f32 v[60:61], v[60:61], v[128:129] op_sel_hi:[1,0]
	v_pk_mul_f32 v[62:63], v[62:63], v[128:129] op_sel_hi:[1,0]
	v_pk_mul_f32 v[198:199], v[56:57], v[128:129] op_sel_hi:[1,0]
	v_pk_mul_f32 v[200:201], v[58:59], v[128:129] op_sel_hi:[1,0]
	v_pk_fma_f32 v[56:57], v[70:71], v[62:63], v[138:139]
	v_pk_fma_f32 v[58:59], v[68:69], v[60:61], v[174:175]
	v_pk_fma_f32 v[60:61], v[66:67], v[200:201], v[140:141]
	v_pk_fma_f32 v[62:63], v[64:65], v[198:199], v[176:177]
	v_cvt_pk_f16_f32 v138, v58, v59
	v_cvt_pk_f16_f32 v139, v56, v57
	v_cvt_pk_f16_f32 v140, v62, v63
	v_cvt_pk_f16_f32 v141, v60, v61
	global_store_dwordx4 v[208:209], v[138:141], off offset:256
	s_nop 0
	v_cvt_f32_f16_e32 v174, v192
	v_cvt_f32_f16_e32 v138, v190
	v_cvt_f32_f16_sdwa v139, v190 dst_sel:DWORD dst_unused:UNUSED_PAD src0_sel:WORD_1
	v_cvt_f32_f16_e32 v140, v191
	v_cvt_f32_f16_sdwa v141, v191 dst_sel:DWORD dst_unused:UNUSED_PAD src0_sel:WORD_1
	v_cvt_f32_f16_e32 v176, v193
	v_cvt_f32_f16_sdwa v177, v193 dst_sel:DWORD dst_unused:UNUSED_PAD src0_sel:WORD_1
	v_mul_f32_e32 v59, v59, v59
	v_mul_f32_e32 v57, v57, v57
	v_mul_f32_e32 v63, v63, v63
	v_mul_f32_e32 v61, v61, v61
	v_fmac_f32_e32 v59, v58, v58
	v_fmac_f32_e32 v57, v56, v56
	v_fmac_f32_e32 v63, v62, v62
	v_fmac_f32_e32 v61, v60, v60
	v_add_f32_e32 v56, v59, v57
	v_add_f32_e32 v57, v63, v61
	v_add_f32_e32 v56, v56, v57
	v_cvt_f32_f16_e32 v60, v75
	v_cvt_f32_f16_sdwa v61, v75 dst_sel:DWORD dst_unused:UNUSED_PAD src0_sel:WORD_1
	v_fmamk_f32 v128, v163, 0x3b2aaaab, v227
	v_mul_f32_e32 v175, 0x4b800000, v128
	v_cmp_gt_f32_e32 vcc, s36, v128
	s_nop 1
	v_cndmask_b32_e32 v128, v128, v175, vcc
	v_rsq_f32_e32 v128, v128
	v_cvt_f32_f16_sdwa v175, v192 dst_sel:DWORD dst_unused:UNUSED_PAD src0_sel:WORD_1
	v_mul_f32_e32 v190, 0x45800000, v128
	v_cndmask_b32_e32 v128, v128, v190, vcc
	v_pk_mul_f32 v[190:191], v[52:53], v[128:129] op_sel_hi:[1,0]
	v_pk_mul_f32 v[52:53], v[54:55], v[128:129] op_sel_hi:[1,0]
	v_pk_mul_f32 v[192:193], v[48:49], v[128:129] op_sel_hi:[1,0]
	v_pk_mul_f32 v[48:49], v[50:51], v[128:129] op_sel_hi:[1,0]
	v_pk_fma_f32 v[52:53], v[70:71], v[52:53], v[140:141]
	v_pk_fma_f32 v[54:55], v[68:69], v[190:191], v[138:139]
	v_pk_fma_f32 v[48:49], v[66:67], v[48:49], v[176:177]
	v_pk_fma_f32 v[50:51], v[64:65], v[192:193], v[174:175]
	v_cvt_pk_f16_f32 v138, v54, v55
	v_cvt_pk_f16_f32 v139, v52, v53
	v_cvt_pk_f16_f32 v140, v50, v51
	v_cvt_pk_f16_f32 v141, v48, v49
	global_store_dwordx4 v[212:213], v[138:141], off offset:256
	s_nop 0
	v_cvt_f32_f16_e32 v174, v196
	v_cvt_f32_f16_e32 v138, v194
	v_cvt_f32_f16_sdwa v139, v194 dst_sel:DWORD dst_unused:UNUSED_PAD src0_sel:WORD_1
	v_cvt_f32_f16_e32 v140, v195
	v_cvt_f32_f16_sdwa v141, v195 dst_sel:DWORD dst_unused:UNUSED_PAD src0_sel:WORD_1
	v_cvt_f32_f16_e32 v176, v197
	v_cvt_f32_f16_sdwa v177, v197 dst_sel:DWORD dst_unused:UNUSED_PAD src0_sel:WORD_1
	v_fmamk_f32 v128, v165, 0x3b2aaaab, v227
	v_mul_f32_e32 v175, 0x4b800000, v128
	v_cmp_gt_f32_e32 vcc, s36, v128
	s_nop 1
	v_cndmask_b32_e32 v128, v128, v175, vcc
	v_rsq_f32_e32 v128, v128
	v_cvt_f32_f16_sdwa v175, v196 dst_sel:DWORD dst_unused:UNUSED_PAD src0_sel:WORD_1
	v_mul_f32_e32 v190, 0x45800000, v128
	v_cndmask_b32_e32 v128, v128, v190, vcc
	v_pk_mul_f32 v[190:191], v[44:45], v[128:129] op_sel_hi:[1,0]
	v_pk_mul_f32 v[44:45], v[46:47], v[128:129] op_sel_hi:[1,0]
	v_pk_mul_f32 v[192:193], v[40:41], v[128:129] op_sel_hi:[1,0]
	v_pk_mul_f32 v[40:41], v[42:43], v[128:129] op_sel_hi:[1,0]
	v_pk_fma_f32 v[44:45], v[70:71], v[44:45], v[140:141]
	v_pk_fma_f32 v[46:47], v[68:69], v[190:191], v[138:139]
	v_pk_fma_f32 v[40:41], v[66:67], v[40:41], v[176:177]
	v_pk_fma_f32 v[42:43], v[64:65], v[192:193], v[174:175]
	v_cvt_pk_f16_f32 v138, v46, v47
	v_cvt_pk_f16_f32 v139, v44, v45
	v_cvt_pk_f16_f32 v140, v42, v43
	v_cvt_pk_f16_f32 v141, v40, v41
	global_store_dwordx4 v[214:215], v[138:141], off offset:256
	s_nop 0
	v_cvt_f32_f16_e32 v174, v244
	v_cvt_f32_f16_e32 v138, v242
	v_cvt_f32_f16_sdwa v139, v242 dst_sel:DWORD dst_unused:UNUSED_PAD src0_sel:WORD_1
	v_cvt_f32_f16_e32 v140, v243
	v_cvt_f32_f16_sdwa v141, v243 dst_sel:DWORD dst_unused:UNUSED_PAD src0_sel:WORD_1
	v_cvt_f32_f16_e32 v176, v245
	v_cvt_f32_f16_sdwa v177, v245 dst_sel:DWORD dst_unused:UNUSED_PAD src0_sel:WORD_1
	v_fmamk_f32 v128, v167, 0x3b2aaaab, v227
	v_mul_f32_e32 v175, 0x4b800000, v128
	v_cmp_gt_f32_e32 vcc, s36, v128
	s_nop 1
	v_cndmask_b32_e32 v128, v128, v175, vcc
	v_rsq_f32_e32 v128, v128
	v_cvt_f32_f16_sdwa v175, v244 dst_sel:DWORD dst_unused:UNUSED_PAD src0_sel:WORD_1
	v_mul_f32_e32 v190, 0x45800000, v128
	v_cndmask_b32_e32 v128, v128, v190, vcc
	v_pk_mul_f32 v[190:191], v[36:37], v[128:129] op_sel_hi:[1,0]
	v_pk_mul_f32 v[36:37], v[38:39], v[128:129] op_sel_hi:[1,0]
	v_pk_mul_f32 v[192:193], v[32:33], v[128:129] op_sel_hi:[1,0]
	v_pk_mul_f32 v[32:33], v[34:35], v[128:129] op_sel_hi:[1,0]
	v_pk_fma_f32 v[36:37], v[70:71], v[36:37], v[140:141]
	v_pk_fma_f32 v[38:39], v[68:69], v[190:191], v[138:139]
	v_pk_fma_f32 v[32:33], v[66:67], v[32:33], v[176:177]
	v_pk_fma_f32 v[34:35], v[64:65], v[192:193], v[174:175]
	v_cvt_pk_f16_f32 v138, v38, v39
	v_cvt_pk_f16_f32 v139, v36, v37
	v_cvt_pk_f16_f32 v140, v34, v35
; __device__ __forceinline__ unsigned pk_f16(float lo, float hi) { f32x2 v = {lo, hi}; f16x2_t h = __builtin_convertvector(v, f16x2_t); return __builtin_bit_cast(unsigned, h); }
; __device__ __forceinline__ f32x2 up_f16(unsigned w) { return __builtin_convertvector(__builtin_bit_cast(f16x2_t, w), f32x2); }
;     __device__ __forceinline__ void operator()(const f32x4 (&acc)[2][2][4][2], const Unit& u, int wr, int wc, int fr, int fq) const {
;     ...
;             for (int ai = 0; ai < 2; ++ai) {
; #pragma unroll
;                 for (int m = 0; m < 4; ++m) { const size_t off = (size_t)(row0 + ai * HALF + m * 16) * 1024 + col0 + bj * HALF;
;                     float rc = 1.0f; if constexpr (GN) rc = rsqrtf(gss[2 * 32768 + row0 + ai * HALF + m * 16] * (1.0f / 384.0f) + 1e-6f);
;                     const u32x4 q = pq[ai][m];
;                     const f32x2 qa_ = up_f16(q.x), qb_ = up_f16(q.y), qc_ = up_f16(q.z), qd_ = up_f16(q.w);
;                     const f32x4 x0 = (f32x4){qa_[0], qa_[1], qb_[0], qb_[1]} + gv[0] * (acc[ai][bj][m][0] * rc),
;                                 x1 = (f32x4){qc_[0], qc_[1], qd_[0], qd_[1]} + gv[1] * (acc[ai][bj][m][1] * rc);
;                     { u32x4 wx; wx.x = pk_f16(x0[0], x0[1]); wx.y = pk_f16(x0[2], x0[3]); wx.z = pk_f16(x1[0], x1[1]); wx.w = pk_f16(x1[2], x1[3]); *(u32x4*)(out + off) = wx; }
;                     ss[ai][m] += ((x0[0] * x0[0] + x0[1] * x0[1]) + (x0[2] * x0[2] + x0[3] * x0[3])) + ((x1[0] * x1[0] + x1[1] * x1[1]) + (x1[2] * x1[2] + x1[3] * x1[3]));
;                 }
;                 asm volatile("" ::: "memory");
;             }
;         }
; #pragma unroll
;         for (int ai = 0; ai < 2; ++ai)
; #pragma unroll
;             for (int m = 0; m < 4; ++m) { float t = ss[ai][m]; t += __shfl_xor(t, 16); t += __shfl_xor(t, 32);
;                 if (fq == 0) atomicAdd(rowss + row0 + ai * HALF + m * 16, t); }
	v_cvt_pk_f16_f32 v141, v32, v33
	global_store_dwordx4 v[158:159], v[138:141], off offset:256
	s_nop 0
	v_fmamk_f32 v128, v169, 0x3b2aaaab, v227
	v_mul_f32_e32 v141, 0x4b800000, v128
	v_cmp_gt_f32_e32 vcc, s36, v128
	v_cvt_f32_f16_e32 v138, v84
	v_cvt_f32_f16_sdwa v139, v84 dst_sel:DWORD dst_unused:UNUSED_PAD src0_sel:WORD_1
	v_cndmask_b32_e32 v128, v128, v141, vcc
	v_rsq_f32_e32 v128, v128
	v_cvt_f32_f16_e32 v84, v85
	v_cvt_f32_f16_sdwa v85, v85 dst_sel:DWORD dst_unused:UNUSED_PAD src0_sel:WORD_1
	v_cvt_f32_f16_e32 v140, v86
	v_cvt_f32_f16_sdwa v141, v86 dst_sel:DWORD dst_unused:UNUSED_PAD src0_sel:WORD_1
	v_cvt_f32_f16_e32 v86, v87
	v_cvt_f32_f16_sdwa v87, v87 dst_sel:DWORD dst_unused:UNUSED_PAD src0_sel:WORD_1
	v_mul_f32_e32 v158, 0x45800000, v128
	v_cndmask_b32_e32 v128, v128, v158, vcc
	v_pk_mul_f32 v[158:159], v[28:29], v[128:129] op_sel_hi:[1,0]
	v_pk_mul_f32 v[28:29], v[30:31], v[128:129] op_sel_hi:[1,0]
	v_pk_mul_f32 v[174:175], v[24:25], v[128:129] op_sel_hi:[1,0]
	v_pk_mul_f32 v[24:25], v[26:27], v[128:129] op_sel_hi:[1,0]
	v_pk_fma_f32 v[28:29], v[70:71], v[28:29], v[84:85]
	v_pk_fma_f32 v[30:31], v[68:69], v[158:159], v[138:139]
	v_pk_fma_f32 v[24:25], v[66:67], v[24:25], v[86:87]
	v_pk_fma_f32 v[26:27], v[64:65], v[174:175], v[140:141]
	v_cvt_pk_f16_f32 v84, v30, v31
	v_cvt_pk_f16_f32 v85, v28, v29
	v_cvt_pk_f16_f32 v86, v26, v27
	v_cvt_pk_f16_f32 v87, v24, v25
	global_store_dwordx4 v[218:219], v[84:87], off offset:256
	s_nop 0
	s_nop 0
	v_cvt_f32_f16_e32 v84, v80
	v_cvt_f32_f16_sdwa v85, v80 dst_sel:DWORD dst_unused:UNUSED_PAD src0_sel:WORD_1
	v_cvt_f32_f16_e32 v80, v81
	v_cvt_f32_f16_sdwa v81, v81 dst_sel:DWORD dst_unused:UNUSED_PAD src0_sel:WORD_1
	v_cvt_f32_f16_e32 v86, v82
	v_fmamk_f32 v87, v171, 0x3b2aaaab, v227
	v_mul_f32_e32 v128, 0x4b800000, v87
	v_cmp_gt_f32_e32 vcc, s36, v87
	s_nop 1
	v_cndmask_b32_e32 v87, v87, v128, vcc
	v_rsq_f32_e32 v128, v87
	v_cvt_f32_f16_sdwa v87, v82 dst_sel:DWORD dst_unused:UNUSED_PAD src0_sel:WORD_1
	v_cvt_f32_f16_e32 v82, v83
	v_cvt_f32_f16_sdwa v83, v83 dst_sel:DWORD dst_unused:UNUSED_PAD src0_sel:WORD_1
	v_mul_f32_e32 v138, 0x45800000, v128
	v_cndmask_b32_e32 v128, v128, v138, vcc
	v_pk_mul_f32 v[138:139], v[20:21], v[128:129] op_sel_hi:[1,0]
	v_pk_mul_f32 v[20:21], v[22:23], v[128:129] op_sel_hi:[1,0]
	v_pk_mul_f32 v[140:141], v[16:17], v[128:129] op_sel_hi:[1,0]
	v_pk_mul_f32 v[16:17], v[18:19], v[128:129] op_sel_hi:[1,0]
	v_pk_fma_f32 v[20:21], v[70:71], v[20:21], v[80:81]
	v_pk_fma_f32 v[22:23], v[68:69], v[138:139], v[84:85]
	v_pk_fma_f32 v[16:17], v[66:67], v[16:17], v[82:83]
	v_pk_fma_f32 v[18:19], v[64:65], v[140:141], v[86:87]
	v_cvt_pk_f16_f32 v80, v22, v23
	v_cvt_pk_f16_f32 v81, v20, v21
	v_cvt_pk_f16_f32 v82, v18, v19
	v_cvt_pk_f16_f32 v83, v16, v17
	global_store_dwordx4 v[220:221], v[80:83], off offset:256
	s_nop 0
	s_nop 0
	v_cvt_f32_f16_e32 v80, v76
	v_cvt_f32_f16_sdwa v81, v76 dst_sel:DWORD dst_unused:UNUSED_PAD src0_sel:WORD_1
	v_cvt_f32_f16_e32 v76, v77
	v_cvt_f32_f16_sdwa v77, v77 dst_sel:DWORD dst_unused:UNUSED_PAD src0_sel:WORD_1
	v_cvt_f32_f16_e32 v82, v78
	v_fmamk_f32 v83, v173, 0x3b2aaaab, v227
	v_mov_b32_e32 v163, v129
	v_mov_b32_e32 v165, v129
	v_mov_b32_e32 v167, v129
	v_mov_b32_e32 v169, v129
	v_mov_b32_e32 v171, v129
	v_mov_b32_e32 v173, v129
	v_mul_f32_e32 v84, 0x4b800000, v83
	v_cmp_gt_f32_e32 vcc, s36, v83
	s_nop 1
	v_cndmask_b32_e32 v83, v83, v84, vcc
	v_rsq_f32_e32 v84, v83
	v_cvt_f32_f16_sdwa v83, v78 dst_sel:DWORD dst_unused:UNUSED_PAD src0_sel:WORD_1
	v_cvt_f32_f16_e32 v78, v79
	v_cvt_f32_f16_sdwa v79, v79 dst_sel:DWORD dst_unused:UNUSED_PAD src0_sel:WORD_1
	v_mul_f32_e32 v85, 0x45800000, v84
	v_cndmask_b32_e32 v84, v84, v85, vcc
	v_pk_mul_f32 v[86:87], v[12:13], v[84:85] op_sel_hi:[1,0]
	v_pk_mul_f32 v[12:13], v[14:15], v[84:85] op_sel_hi:[1,0]
	v_pk_mul_f32 v[138:139], v[8:9], v[84:85] op_sel_hi:[1,0]
	v_pk_mul_f32 v[8:9], v[10:11], v[84:85] op_sel_hi:[1,0]
	v_pk_fma_f32 v[12:13], v[70:71], v[12:13], v[76:77]
	v_pk_fma_f32 v[14:15], v[68:69], v[86:87], v[80:81]
	v_pk_fma_f32 v[8:9], v[66:67], v[8:9], v[78:79]
	v_pk_fma_f32 v[10:11], v[64:65], v[138:139], v[82:83]
	v_cvt_pk_f16_f32 v76, v14, v15
	v_cvt_pk_f16_f32 v77, v12, v13
	v_cvt_pk_f16_f32 v78, v10, v11
	v_cvt_pk_f16_f32 v79, v8, v9
	global_store_dwordx4 v[222:223], v[76:79], off offset:256
	global_load_dword v82, v[188:189], off offset:704
	v_mul_f32_e32 v80, v127, v127
	v_and_b32_e32 v77, 64, v230
	v_xor_b32_e32 v76, 16, v230
	v_add_u32_e32 v77, 64, v77
	v_xor_b32_e32 v78, 32, v230
	v_cmp_lt_i32_e32 vcc, v76, v77
	v_mul_f32_e32 v79, v121, v121
	v_mul_f32_e32 v81, v123, v123
	v_cndmask_b32_e32 v76, v230, v76, vcc
	v_cmp_lt_i32_e32 vcc, v78, v77
	v_lshlrev_b32_e32 v77, 2, v76
	v_fmac_f32_e32 v79, v120, v120
	v_cndmask_b32_e32 v78, v230, v78, vcc
	v_lshlrev_b32_e32 v76, 2, v78
	v_mul_f32_e32 v78, v125, v125
	v_fmac_f32_e32 v78, v124, v124
	v_fmac_f32_e32 v80, v126, v126
	v_fmac_f32_e32 v81, v122, v122
	v_add_f32_e32 v78, v78, v79
	v_add_f32_e32 v79, v80, v81
	v_add_f32_e32 v83, v78, v79
	v_add_f32_e32 v56, v83, v56
	ds_bpermute_b32 v57, v77, v56
	v_cvt_f32_f16_e32 v78, v72
	v_cvt_f32_f16_sdwa v79, v72 dst_sel:DWORD dst_unused:UNUSED_PAD src0_sel:WORD_1
	v_cvt_f32_f16_e32 v72, v73
	v_cvt_f32_f16_sdwa v73, v73 dst_sel:DWORD dst_unused:UNUSED_PAD src0_sel:WORD_1
	v_cvt_f32_f16_e32 v80, v74
	v_cvt_f32_f16_sdwa v81, v74 dst_sel:DWORD dst_unused:UNUSED_PAD src0_sel:WORD_1
	s_waitcnt vmcnt(0)
	v_fmamk_f32 v58, v82, 0x3b2aaaab, v227
	v_mul_f32_e32 v59, 0x4b800000, v58
	v_cmp_gt_f32_e32 vcc, s36, v58
	s_nop 1
	v_cndmask_b32_e32 v58, v58, v59, vcc
	v_rsq_f32_e32 v59, v58
	s_waitcnt lgkmcnt(0)
	v_add_f32_e32 v58, v56, v57
	v_mul_f32_e32 v56, 0x45800000, v59
	v_cndmask_b32_e32 v56, v59, v56, vcc
	v_pk_mul_f32 v[4:5], v[4:5], v[56:57] op_sel_hi:[1,0]
	v_pk_mul_f32 v[6:7], v[6:7], v[56:57] op_sel_hi:[1,0]
	v_pk_mul_f32 v[0:1], v[0:1], v[56:57] op_sel_hi:[1,0]
	v_pk_mul_f32 v[2:3], v[2:3], v[56:57] op_sel_hi:[1,0]
	v_pk_fma_f32 v[6:7], v[70:71], v[6:7], v[72:73]
	v_pk_fma_f32 v[56:57], v[68:69], v[4:5], v[78:79]
	v_pk_fma_f32 v[2:3], v[66:67], v[2:3], v[60:61]
	v_pk_fma_f32 v[4:5], v[64:65], v[0:1], v[80:81]
	v_cvt_pk_f16_f32 v60, v56, v57
	v_cvt_pk_f16_f32 v61, v6, v7
	v_cvt_pk_f16_f32 v62, v4, v5
	v_cvt_pk_f16_f32 v63, v2, v3
	ds_bpermute_b32 v59, v76, v58
	global_store_dwordx4 v[160:161], v[60:63], off offset:256
	v_lshl_add_u64 v[0:1], v[186:187], 2, s[46:47]
	s_and_saveexec_b64 s[0:1], s[40:41]
	s_cbranch_execz .LBB0_808
	s_waitcnt lgkmcnt(0)
	v_add_f32_e32 v58, v58, v59
	global_atomic_add_f32 v[0:1], v58, off
